# O3 wide epilogue: y0b residual loads hoisted ahead of the 16 passes, counted vmcnt (same scheme as E3)
# speedup vs baseline: 1.0140x; 1.0065x over previous
;   DI u16* y0b() const { return (u16*)(ws + WS_y0b); }
;   DI float* pre() const { return (float*)(ws + WS_pre); }
; DI float bflo(unsigned v) { return __uint_as_float(v << 16); }
; DI float bfhi(unsigned v) { return __uint_as_float(v & 0xffff0000u); }
; DI int otid() { int t = threadIdx.x; asm volatile("" : "+v"(t)); return t; }
; DI void st_bf4(u16* d, float a, float b, float c, float e) { *(uint2*)d = pack4(a, b, c, e); }
;   const int tid = otid(), c4 = (tid & 31) * 4;
;   for (int pp = 0; pp < npass; ++pp) {
;     const int row = pp * 8 + (tid >> 5);
;     const int tok = mt * 128 + row0 + row;
;     const int col = nt * 128 + c4;
;     float4 v = *(const float4*)(Cs + row * CS_LD + c4);
;     float4 x;
;     if (layer == 0) { const f32x4 t = __builtin_nontemporal_load((const f32x4*)(tok < TP ? p.x_prompt + (size_t)tok * 1024 + col : p.x_sample + (size_t)(tok - TP) * 1024 + col)); x = make_float4(t[0], t[1], t[2], t[3]); }
;     else { const uint2 yb = *(const uint2*)(p.y0b() + (size_t)tok * 1024 + col); x = make_float4(bflo(yb.x), bfhi(yb.x), bflo(yb.y), bfhi(yb.y)); }
;     st_bf4((u16*)p.pre() + (size_t)tok * 1024 + col, ALPHA * x.x + v.x, ALPHA * x.y + v.y, ALPHA * x.z + v.z, ALPHA * x.w + v.w);
;   }
.LBB0_2049:
	s_or_b64 exec, exec, s[0:1]
	v_mov_b32_e32 v0, v186
	s_waitcnt lgkmcnt(0)
	s_barrier
	v_lshlrev_b32_e32 v220, 2, v186
	v_and_b32_e32 v220, 0x7c, v220
	v_ashrrev_i32_e32 v221, 5, v186
	v_mul_lo_u32 v222, v221, s26
	v_lshl_add_u32 v222, v220, 2, v222
	v_lshlrev_b32_e32 v224, 11, v221
	v_lshl_add_u32 v224, v220, 1, v224
	s_lshl_b32 s29, s27, 11
	s_add_u32 s0, s8, s29
	s_addc_u32 s1, s9, 0
	s_add_u32 s2, s10, s29
	s_addc_u32 s3, s11, 0
	s_lshl_b32 s29, s28, 1
	s_add_u32 s0, s0, s29
	s_addc_u32 s1, s1, 0
	s_add_u32 s2, s2, s29
	s_addc_u32 s3, s3, 0
	ds_read_b128 v[228:231], v222
	ds_read_b128 v[232:235], v222 offset:4224
	ds_read_b128 v[236:239], v222 offset:8448
	ds_read_b128 v[240:243], v222 offset:12672
	global_load_dwordx2 v[154:155], v224, s[0:1] offset:256
	s_add_u32 s0, s0, 0x4000
	s_addc_u32 s1, s1, 0
	global_load_dwordx2 v[156:157], v224, s[0:1] offset:256
	s_add_u32 s0, s0, 0x4000
	s_addc_u32 s1, s1, 0
	global_load_dwordx2 v[158:159], v224, s[0:1] offset:256
	s_add_u32 s0, s0, 0x4000
	s_addc_u32 s1, s1, 0
	global_load_dwordx2 v[160:161], v224, s[0:1] offset:256
	s_add_u32 s0, s0, 0x4000
	s_addc_u32 s1, s1, 0
	global_load_dwordx2 v[162:163], v224, s[0:1] offset:256
	s_add_u32 s0, s0, 0x4000
	s_addc_u32 s1, s1, 0
	global_load_dwordx2 v[164:165], v224, s[0:1] offset:256
	s_add_u32 s0, s0, 0x4000
	s_addc_u32 s1, s1, 0
	global_load_dwordx2 v[166:167], v224, s[0:1] offset:256
	s_add_u32 s0, s0, 0x4000
	s_addc_u32 s1, s1, 0
	global_load_dwordx2 v[168:169], v224, s[0:1] offset:256
	s_add_u32 s0, s0, 0x4000
	s_addc_u32 s1, s1, 0
	global_load_dwordx2 v[170:171], v224, s[0:1] offset:256
	s_add_u32 s0, s0, 0x4000
	s_addc_u32 s1, s1, 0
	global_load_dwordx2 v[172:173], v224, s[0:1] offset:256
	s_add_u32 s0, s0, 0x4000
	s_addc_u32 s1, s1, 0
	global_load_dwordx2 v[174:175], v224, s[0:1] offset:256
	s_add_u32 s0, s0, 0x4000
	s_addc_u32 s1, s1, 0
	global_load_dwordx2 v[176:177], v224, s[0:1] offset:256
	s_add_u32 s0, s0, 0x4000
	s_addc_u32 s1, s1, 0
	global_load_dwordx2 v[178:179], v224, s[0:1] offset:256
	s_add_u32 s0, s0, 0x4000
	s_addc_u32 s1, s1, 0
	global_load_dwordx2 v[180:181], v224, s[0:1] offset:256
	s_add_u32 s0, s0, 0x4000
	s_addc_u32 s1, s1, 0
	global_load_dwordx2 v[182:183], v224, s[0:1] offset:256
	s_add_u32 s0, s0, 0x4000
	s_addc_u32 s1, s1, 0
	global_load_dwordx2 v[184:185], v224, s[0:1] offset:256
	s_waitcnt vmcnt(15)
	v_lshlrev_b32_e32 v204, 16, v154
	v_and_b32_e32 v205, 0xffff0000, v154
	v_lshlrev_b32_e32 v206, 16, v155
	v_and_b32_e32 v207, 0xffff0000, v155
	s_waitcnt lgkmcnt(3)
	v_pk_fma_f32 v[228:229], v[204:205], s[22:23], v[228:229] op_sel_hi:[1,0,1]
	v_pk_fma_f32 v[230:231], v[206:207], s[22:23], v[230:231] op_sel_hi:[1,0,1]
	v_cvt_pk_bf16_f32 v244, v228, v229
	v_cvt_pk_bf16_f32 v245, v230, v231
	global_store_dwordx2 v224, v[244:245], s[2:3] offset:256
	s_add_u32 s2, s2, 0x4000
	s_addc_u32 s3, s3, 0
	ds_read_b128 v[228:231], v222 offset:16896
	s_waitcnt vmcnt(15)
	v_lshlrev_b32_e32 v208, 16, v156
	v_and_b32_e32 v209, 0xffff0000, v156
	v_lshlrev_b32_e32 v210, 16, v157
	v_and_b32_e32 v211, 0xffff0000, v157
	s_waitcnt lgkmcnt(3)
	v_pk_fma_f32 v[232:233], v[208:209], s[22:23], v[232:233] op_sel_hi:[1,0,1]
	v_pk_fma_f32 v[234:235], v[210:211], s[22:23], v[234:235] op_sel_hi:[1,0,1]
	v_cvt_pk_bf16_f32 v226, v232, v233
	v_cvt_pk_bf16_f32 v227, v234, v235
	global_store_dwordx2 v224, v[226:227], s[2:3] offset:256
	s_add_u32 s2, s2, 0x4000
	s_addc_u32 s3, s3, 0
	ds_read_b128 v[232:235], v222 offset:21120
	s_waitcnt vmcnt(15)
	v_lshlrev_b32_e32 v204, 16, v158
	v_and_b32_e32 v205, 0xffff0000, v158
	v_lshlrev_b32_e32 v206, 16, v159
	v_and_b32_e32 v207, 0xffff0000, v159
	s_waitcnt lgkmcnt(3)
	v_pk_fma_f32 v[236:237], v[204:205], s[22:23], v[236:237] op_sel_hi:[1,0,1]
	v_pk_fma_f32 v[238:239], v[206:207], s[22:23], v[238:239] op_sel_hi:[1,0,1]
	v_cvt_pk_bf16_f32 v244, v236, v237
	v_cvt_pk_bf16_f32 v245, v238, v239
	global_store_dwordx2 v224, v[244:245], s[2:3] offset:256
	s_add_u32 s2, s2, 0x4000
	s_addc_u32 s3, s3, 0
	ds_read_b128 v[236:239], v222 offset:25344
	s_waitcnt vmcnt(15)
	v_lshlrev_b32_e32 v208, 16, v160
	v_and_b32_e32 v209, 0xffff0000, v160
	v_lshlrev_b32_e32 v210, 16, v161
	v_and_b32_e32 v211, 0xffff0000, v161
	s_waitcnt lgkmcnt(3)
	v_pk_fma_f32 v[240:241], v[208:209], s[22:23], v[240:241] op_sel_hi:[1,0,1]
	v_pk_fma_f32 v[242:243], v[210:211], s[22:23], v[242:243] op_sel_hi:[1,0,1]
	v_cvt_pk_bf16_f32 v226, v240, v241
	v_cvt_pk_bf16_f32 v227, v242, v243
	global_store_dwordx2 v224, v[226:227], s[2:3] offset:256
	s_add_u32 s2, s2, 0x4000
	s_addc_u32 s3, s3, 0
	ds_read_b128 v[240:243], v222 offset:29568
	s_waitcnt vmcnt(15)
	v_lshlrev_b32_e32 v204, 16, v162
	v_and_b32_e32 v205, 0xffff0000, v162
	v_lshlrev_b32_e32 v206, 16, v163
	v_and_b32_e32 v207, 0xffff0000, v163
	s_waitcnt lgkmcnt(3)
	v_pk_fma_f32 v[228:229], v[204:205], s[22:23], v[228:229] op_sel_hi:[1,0,1]
	v_pk_fma_f32 v[230:231], v[206:207], s[22:23], v[230:231] op_sel_hi:[1,0,1]
	v_cvt_pk_bf16_f32 v244, v228, v229
	v_cvt_pk_bf16_f32 v245, v230, v231
	global_store_dwordx2 v224, v[244:245], s[2:3] offset:256
	s_add_u32 s2, s2, 0x4000
	s_addc_u32 s3, s3, 0
	ds_read_b128 v[228:231], v222 offset:33792
	s_waitcnt vmcnt(15)
	v_lshlrev_b32_e32 v208, 16, v164
	v_and_b32_e32 v209, 0xffff0000, v164
	v_lshlrev_b32_e32 v210, 16, v165
	v_and_b32_e32 v211, 0xffff0000, v165
	s_waitcnt lgkmcnt(3)
	v_pk_fma_f32 v[232:233], v[208:209], s[22:23], v[232:233] op_sel_hi:[1,0,1]
	v_pk_fma_f32 v[234:235], v[210:211], s[22:23], v[234:235] op_sel_hi:[1,0,1]
	v_cvt_pk_bf16_f32 v226, v232, v233
	v_cvt_pk_bf16_f32 v227, v234, v235
	global_store_dwordx2 v224, v[226:227], s[2:3] offset:256
	s_add_u32 s2, s2, 0x4000
	s_addc_u32 s3, s3, 0
	ds_read_b128 v[232:235], v222 offset:38016
	s_waitcnt vmcnt(15)
;   DI u16* y0b() const { return (u16*)(ws + WS_y0b); }
;   DI float* pre() const { return (float*)(ws + WS_pre); }
; DI float bflo(unsigned v) { return __uint_as_float(v << 16); }
; DI float bfhi(unsigned v) { return __uint_as_float(v & 0xffff0000u); }
; DI int otid() { int t = threadIdx.x; asm volatile("" : "+v"(t)); return t; }
; DI void st_bf4(u16* d, float a, float b, float c, float e) { *(uint2*)d = pack4(a, b, c, e); }
;   const int tid = otid(), c4 = (tid & 31) * 4;
;   for (int pp = 0; pp < npass; ++pp) {
;     const int row = pp * 8 + (tid >> 5);
;     const int tok = mt * 128 + row0 + row;
;     const int col = nt * 128 + c4;
;     float4 v = *(const float4*)(Cs + row * CS_LD + c4);
;     float4 x;
;     if (layer == 0) { const f32x4 t = __builtin_nontemporal_load((const f32x4*)(tok < TP ? p.x_prompt + (size_t)tok * 1024 + col : p.x_sample + (size_t)(tok - TP) * 1024 + col)); x = make_float4(t[0], t[1], t[2], t[3]); }
;     else { const uint2 yb = *(const uint2*)(p.y0b() + (size_t)tok * 1024 + col); x = make_float4(bflo(yb.x), bfhi(yb.x), bflo(yb.y), bfhi(yb.y)); }
;     st_bf4((u16*)p.pre() + (size_t)tok * 1024 + col, ALPHA * x.x + v.x, ALPHA * x.y + v.y, ALPHA * x.z + v.z, ALPHA * x.w + v.w);
;   }
; __global__ void __launch_bounds__(256, 2) fwd_megakernel(Params p) {
;     ...
;   for (TileSched ts = tile_sched(128 * 4); ts.t < ts.hi; ts.t += ts.step) {
;     const int mt = ts.t >> 2, n2 = ts.t & 3;
	v_lshlrev_b32_e32 v204, 16, v166
	v_and_b32_e32 v205, 0xffff0000, v166
	v_lshlrev_b32_e32 v206, 16, v167
	v_and_b32_e32 v207, 0xffff0000, v167
	s_waitcnt lgkmcnt(3)
	v_pk_fma_f32 v[236:237], v[204:205], s[22:23], v[236:237] op_sel_hi:[1,0,1]
	v_pk_fma_f32 v[238:239], v[206:207], s[22:23], v[238:239] op_sel_hi:[1,0,1]
	v_cvt_pk_bf16_f32 v244, v236, v237
	v_cvt_pk_bf16_f32 v245, v238, v239
	global_store_dwordx2 v224, v[244:245], s[2:3] offset:256
	s_add_u32 s2, s2, 0x4000
	s_addc_u32 s3, s3, 0
	ds_read_b128 v[236:239], v222 offset:42240
	s_waitcnt vmcnt(15)
	v_lshlrev_b32_e32 v208, 16, v168
	v_and_b32_e32 v209, 0xffff0000, v168
	v_lshlrev_b32_e32 v210, 16, v169
	v_and_b32_e32 v211, 0xffff0000, v169
	s_waitcnt lgkmcnt(3)
	v_pk_fma_f32 v[240:241], v[208:209], s[22:23], v[240:241] op_sel_hi:[1,0,1]
	v_pk_fma_f32 v[242:243], v[210:211], s[22:23], v[242:243] op_sel_hi:[1,0,1]
	v_cvt_pk_bf16_f32 v226, v240, v241
	v_cvt_pk_bf16_f32 v227, v242, v243
	global_store_dwordx2 v224, v[226:227], s[2:3] offset:256
	s_add_u32 s2, s2, 0x4000
	s_addc_u32 s3, s3, 0
	ds_read_b128 v[240:243], v222 offset:46464
	s_waitcnt vmcnt(15)
	v_lshlrev_b32_e32 v204, 16, v170
	v_and_b32_e32 v205, 0xffff0000, v170
	v_lshlrev_b32_e32 v206, 16, v171
	v_and_b32_e32 v207, 0xffff0000, v171
	s_waitcnt lgkmcnt(3)
	v_pk_fma_f32 v[228:229], v[204:205], s[22:23], v[228:229] op_sel_hi:[1,0,1]
	v_pk_fma_f32 v[230:231], v[206:207], s[22:23], v[230:231] op_sel_hi:[1,0,1]
	v_cvt_pk_bf16_f32 v244, v228, v229
	v_cvt_pk_bf16_f32 v245, v230, v231
	global_store_dwordx2 v224, v[244:245], s[2:3] offset:256
	s_add_u32 s2, s2, 0x4000
	s_addc_u32 s3, s3, 0
	ds_read_b128 v[228:231], v222 offset:50688
	s_waitcnt vmcnt(15)
	v_lshlrev_b32_e32 v208, 16, v172
	v_and_b32_e32 v209, 0xffff0000, v172
	v_lshlrev_b32_e32 v210, 16, v173
	v_and_b32_e32 v211, 0xffff0000, v173
	s_waitcnt lgkmcnt(3)
	v_pk_fma_f32 v[232:233], v[208:209], s[22:23], v[232:233] op_sel_hi:[1,0,1]
	v_pk_fma_f32 v[234:235], v[210:211], s[22:23], v[234:235] op_sel_hi:[1,0,1]
	v_cvt_pk_bf16_f32 v226, v232, v233
	v_cvt_pk_bf16_f32 v227, v234, v235
	global_store_dwordx2 v224, v[226:227], s[2:3] offset:256
	s_add_u32 s2, s2, 0x4000
	s_addc_u32 s3, s3, 0
	ds_read_b128 v[232:235], v222 offset:54912
	s_waitcnt vmcnt(15)
	v_lshlrev_b32_e32 v204, 16, v174
	v_and_b32_e32 v205, 0xffff0000, v174
	v_lshlrev_b32_e32 v206, 16, v175
	v_and_b32_e32 v207, 0xffff0000, v175
	s_waitcnt lgkmcnt(3)
	v_pk_fma_f32 v[236:237], v[204:205], s[22:23], v[236:237] op_sel_hi:[1,0,1]
	v_pk_fma_f32 v[238:239], v[206:207], s[22:23], v[238:239] op_sel_hi:[1,0,1]
	v_cvt_pk_bf16_f32 v244, v236, v237
	v_cvt_pk_bf16_f32 v245, v238, v239
	global_store_dwordx2 v224, v[244:245], s[2:3] offset:256
	s_add_u32 s2, s2, 0x4000
	s_addc_u32 s3, s3, 0
	ds_read_b128 v[236:239], v222 offset:59136
	s_waitcnt vmcnt(15)
	v_lshlrev_b32_e32 v208, 16, v176
	v_and_b32_e32 v209, 0xffff0000, v176
	v_lshlrev_b32_e32 v210, 16, v177
	v_and_b32_e32 v211, 0xffff0000, v177
	s_waitcnt lgkmcnt(3)
	v_pk_fma_f32 v[240:241], v[208:209], s[22:23], v[240:241] op_sel_hi:[1,0,1]
	v_pk_fma_f32 v[242:243], v[210:211], s[22:23], v[242:243] op_sel_hi:[1,0,1]
	v_cvt_pk_bf16_f32 v226, v240, v241
	v_cvt_pk_bf16_f32 v227, v242, v243
	global_store_dwordx2 v224, v[226:227], s[2:3] offset:256
	s_add_u32 s2, s2, 0x4000
	s_addc_u32 s3, s3, 0
	ds_read_b128 v[240:243], v222 offset:63360
	s_waitcnt vmcnt(15)
	v_lshlrev_b32_e32 v204, 16, v178
	v_and_b32_e32 v205, 0xffff0000, v178
	v_lshlrev_b32_e32 v206, 16, v179
	v_and_b32_e32 v207, 0xffff0000, v179
	s_waitcnt lgkmcnt(3)
	v_pk_fma_f32 v[228:229], v[204:205], s[22:23], v[228:229] op_sel_hi:[1,0,1]
	v_pk_fma_f32 v[230:231], v[206:207], s[22:23], v[230:231] op_sel_hi:[1,0,1]
	v_cvt_pk_bf16_f32 v244, v228, v229
	v_cvt_pk_bf16_f32 v245, v230, v231
	global_store_dwordx2 v224, v[244:245], s[2:3] offset:256
	s_add_u32 s2, s2, 0x4000
	s_addc_u32 s3, s3, 0
	s_waitcnt vmcnt(15)
	v_lshlrev_b32_e32 v208, 16, v180
	v_and_b32_e32 v209, 0xffff0000, v180
	v_lshlrev_b32_e32 v210, 16, v181
	v_and_b32_e32 v211, 0xffff0000, v181
	s_waitcnt lgkmcnt(2)
	v_pk_fma_f32 v[232:233], v[208:209], s[22:23], v[232:233] op_sel_hi:[1,0,1]
	v_pk_fma_f32 v[234:235], v[210:211], s[22:23], v[234:235] op_sel_hi:[1,0,1]
	v_cvt_pk_bf16_f32 v226, v232, v233
	v_cvt_pk_bf16_f32 v227, v234, v235
	global_store_dwordx2 v224, v[226:227], s[2:3] offset:256
	s_add_u32 s2, s2, 0x4000
	s_addc_u32 s3, s3, 0
	s_waitcnt vmcnt(15)
	v_lshlrev_b32_e32 v204, 16, v182
	v_and_b32_e32 v205, 0xffff0000, v182
	v_lshlrev_b32_e32 v206, 16, v183
	v_and_b32_e32 v207, 0xffff0000, v183
	s_waitcnt lgkmcnt(1)
	v_pk_fma_f32 v[236:237], v[204:205], s[22:23], v[236:237] op_sel_hi:[1,0,1]
	v_pk_fma_f32 v[238:239], v[206:207], s[22:23], v[238:239] op_sel_hi:[1,0,1]
	v_cvt_pk_bf16_f32 v244, v236, v237
	v_cvt_pk_bf16_f32 v245, v238, v239
	global_store_dwordx2 v224, v[244:245], s[2:3] offset:256
	s_add_u32 s2, s2, 0x4000
	s_addc_u32 s3, s3, 0
	s_waitcnt vmcnt(15)
	v_lshlrev_b32_e32 v208, 16, v184
	v_and_b32_e32 v209, 0xffff0000, v184
	v_lshlrev_b32_e32 v210, 16, v185
	v_and_b32_e32 v211, 0xffff0000, v185
	s_waitcnt lgkmcnt(0)
	v_pk_fma_f32 v[240:241], v[208:209], s[22:23], v[240:241] op_sel_hi:[1,0,1]
	v_pk_fma_f32 v[242:243], v[210:211], s[22:23], v[242:243] op_sel_hi:[1,0,1]
	v_cvt_pk_bf16_f32 v226, v240, v241
	v_cvt_pk_bf16_f32 v227, v242, v243
	global_store_dwordx2 v224, v[226:227], s[2:3] offset:256
	s_add_i32 s5, s5, s4
	s_add_i32 s19, s19, s23
	s_add_i32 s24, s24, s25
	s_cmp_ge_i32 s5, s18
	s_cbranch_scc1 .LBB0_2056

;   DI u16* y0b() const { return (u16*)(ws + WS_y0b); }
;   DI float* pre() const { return (float*)(ws + WS_pre); }
; DI float bflo(unsigned v) { return __uint_as_float(v << 16); }
; DI float bfhi(unsigned v) { return __uint_as_float(v & 0xffff0000u); }
; DI int otid() { int t = threadIdx.x; asm volatile("" : "+v"(t)); return t; }
; DI void st_bf4(u16* d, float a, float b, float c, float e) { *(uint2*)d = pack4(a, b, c, e); }
;   const int tid = otid(), c4 = (tid & 31) * 4;
;   for (int pp = 0; pp < npass; ++pp) {
;     const int row = pp * 8 + (tid >> 5);
;     const int tok = mt * 128 + row0 + row;
;     const int col = nt * 128 + c4;
;     float4 v = *(const float4*)(Cs + row * CS_LD + c4);
;     float4 x;
;     if (layer == 0) { const f32x4 t = __builtin_nontemporal_load((const f32x4*)(tok < TP ? p.x_prompt + (size_t)tok * 1024 + col : p.x_sample + (size_t)(tok - TP) * 1024 + col)); x = make_float4(t[0], t[1], t[2], t[3]); }
;     else { const uint2 yb = *(const uint2*)(p.y0b() + (size_t)tok * 1024 + col); x = make_float4(bflo(yb.x), bfhi(yb.x), bflo(yb.y), bfhi(yb.y)); }
;     st_bf4((u16*)p.pre() + (size_t)tok * 1024 + col, ALPHA * x.x + v.x, ALPHA * x.y + v.y, ALPHA * x.z + v.z, ALPHA * x.w + v.w);
;   }
.LBB0_2054:
	s_or_b64 exec, exec, s[2:3]
	v_mov_b32_e32 v128, v186
	s_waitcnt lgkmcnt(0)
	s_barrier
	v_lshlrev_b32_e32 v220, 2, v186
	v_and_b32_e32 v220, 0x7c, v220
	v_ashrrev_i32_e32 v221, 5, v186
	v_mul_lo_u32 v222, v221, s26
	v_lshl_add_u32 v222, v220, 2, v222
	v_lshlrev_b32_e32 v224, 11, v221
	v_lshl_add_u32 v224, v220, 1, v224
	s_lshl_b32 s29, s27, 11
	s_add_u32 s0, s8, s29
	s_addc_u32 s1, s9, 0
	s_add_u32 s2, s10, s29
	s_addc_u32 s3, s11, 0
	s_lshl_b32 s29, s28, 1
	s_add_u32 s0, s0, s29
	s_addc_u32 s1, s1, 0
	s_add_u32 s2, s2, s29
	s_addc_u32 s3, s3, 0
	ds_read_b128 v[228:231], v222
	ds_read_b128 v[232:235], v222 offset:4224
	ds_read_b128 v[236:239], v222 offset:8448
	ds_read_b128 v[240:243], v222 offset:12672
	global_load_dwordx2 v[154:155], v224, s[0:1]
	s_add_u32 s0, s0, 0x4000
	s_addc_u32 s1, s1, 0
	global_load_dwordx2 v[156:157], v224, s[0:1]
	s_add_u32 s0, s0, 0x4000
	s_addc_u32 s1, s1, 0
	global_load_dwordx2 v[158:159], v224, s[0:1]
	s_add_u32 s0, s0, 0x4000
	s_addc_u32 s1, s1, 0
	global_load_dwordx2 v[160:161], v224, s[0:1]
	s_add_u32 s0, s0, 0x4000
	s_addc_u32 s1, s1, 0
	global_load_dwordx2 v[162:163], v224, s[0:1]
	s_add_u32 s0, s0, 0x4000
	s_addc_u32 s1, s1, 0
	global_load_dwordx2 v[164:165], v224, s[0:1]
	s_add_u32 s0, s0, 0x4000
	s_addc_u32 s1, s1, 0
	global_load_dwordx2 v[166:167], v224, s[0:1]
	s_add_u32 s0, s0, 0x4000
	s_addc_u32 s1, s1, 0
	global_load_dwordx2 v[168:169], v224, s[0:1]
	s_add_u32 s0, s0, 0x4000
	s_addc_u32 s1, s1, 0
	global_load_dwordx2 v[170:171], v224, s[0:1]
	s_add_u32 s0, s0, 0x4000
	s_addc_u32 s1, s1, 0
	global_load_dwordx2 v[172:173], v224, s[0:1]
	s_add_u32 s0, s0, 0x4000
	s_addc_u32 s1, s1, 0
	global_load_dwordx2 v[174:175], v224, s[0:1]
	s_add_u32 s0, s0, 0x4000
	s_addc_u32 s1, s1, 0
	global_load_dwordx2 v[176:177], v224, s[0:1]
	s_add_u32 s0, s0, 0x4000
	s_addc_u32 s1, s1, 0
	global_load_dwordx2 v[178:179], v224, s[0:1]
	s_add_u32 s0, s0, 0x4000
	s_addc_u32 s1, s1, 0
	global_load_dwordx2 v[180:181], v224, s[0:1]
	s_add_u32 s0, s0, 0x4000
	s_addc_u32 s1, s1, 0
	global_load_dwordx2 v[182:183], v224, s[0:1]
	s_add_u32 s0, s0, 0x4000
	s_addc_u32 s1, s1, 0
	global_load_dwordx2 v[184:185], v224, s[0:1]
	s_waitcnt vmcnt(15)
	v_lshlrev_b32_e32 v204, 16, v154
	v_and_b32_e32 v205, 0xffff0000, v154
	v_lshlrev_b32_e32 v206, 16, v155
	v_and_b32_e32 v207, 0xffff0000, v155
	s_waitcnt lgkmcnt(3)
	v_pk_fma_f32 v[228:229], v[204:205], s[22:23], v[228:229] op_sel_hi:[1,0,1]
	v_pk_fma_f32 v[230:231], v[206:207], s[22:23], v[230:231] op_sel_hi:[1,0,1]
	v_cvt_pk_bf16_f32 v244, v228, v229
	v_cvt_pk_bf16_f32 v245, v230, v231
	global_store_dwordx2 v224, v[244:245], s[2:3]
	s_add_u32 s2, s2, 0x4000
	s_addc_u32 s3, s3, 0
	ds_read_b128 v[228:231], v222 offset:16896
	s_waitcnt vmcnt(15)
	v_lshlrev_b32_e32 v208, 16, v156
	v_and_b32_e32 v209, 0xffff0000, v156
	v_lshlrev_b32_e32 v210, 16, v157
	v_and_b32_e32 v211, 0xffff0000, v157
	s_waitcnt lgkmcnt(3)
	v_pk_fma_f32 v[232:233], v[208:209], s[22:23], v[232:233] op_sel_hi:[1,0,1]
	v_pk_fma_f32 v[234:235], v[210:211], s[22:23], v[234:235] op_sel_hi:[1,0,1]
	v_cvt_pk_bf16_f32 v226, v232, v233
	v_cvt_pk_bf16_f32 v227, v234, v235
	global_store_dwordx2 v224, v[226:227], s[2:3]
	s_add_u32 s2, s2, 0x4000
	s_addc_u32 s3, s3, 0
	ds_read_b128 v[232:235], v222 offset:21120
	s_waitcnt vmcnt(15)
	v_lshlrev_b32_e32 v204, 16, v158
	v_and_b32_e32 v205, 0xffff0000, v158
	v_lshlrev_b32_e32 v206, 16, v159
	v_and_b32_e32 v207, 0xffff0000, v159
	s_waitcnt lgkmcnt(3)
	v_pk_fma_f32 v[236:237], v[204:205], s[22:23], v[236:237] op_sel_hi:[1,0,1]
	v_pk_fma_f32 v[238:239], v[206:207], s[22:23], v[238:239] op_sel_hi:[1,0,1]
	v_cvt_pk_bf16_f32 v244, v236, v237
	v_cvt_pk_bf16_f32 v245, v238, v239
	global_store_dwordx2 v224, v[244:245], s[2:3]
	s_add_u32 s2, s2, 0x4000
	s_addc_u32 s3, s3, 0
	ds_read_b128 v[236:239], v222 offset:25344
	s_waitcnt vmcnt(15)
	v_lshlrev_b32_e32 v208, 16, v160
	v_and_b32_e32 v209, 0xffff0000, v160
	v_lshlrev_b32_e32 v210, 16, v161
	v_and_b32_e32 v211, 0xffff0000, v161
	s_waitcnt lgkmcnt(3)
	v_pk_fma_f32 v[240:241], v[208:209], s[22:23], v[240:241] op_sel_hi:[1,0,1]
	v_pk_fma_f32 v[242:243], v[210:211], s[22:23], v[242:243] op_sel_hi:[1,0,1]
	v_cvt_pk_bf16_f32 v226, v240, v241
	v_cvt_pk_bf16_f32 v227, v242, v243
	global_store_dwordx2 v224, v[226:227], s[2:3]
	s_add_u32 s2, s2, 0x4000
	s_addc_u32 s3, s3, 0
	ds_read_b128 v[240:243], v222 offset:29568
	s_waitcnt vmcnt(15)
	v_lshlrev_b32_e32 v204, 16, v162
	v_and_b32_e32 v205, 0xffff0000, v162
	v_lshlrev_b32_e32 v206, 16, v163
	v_and_b32_e32 v207, 0xffff0000, v163
	s_waitcnt lgkmcnt(3)
	v_pk_fma_f32 v[228:229], v[204:205], s[22:23], v[228:229] op_sel_hi:[1,0,1]
	v_pk_fma_f32 v[230:231], v[206:207], s[22:23], v[230:231] op_sel_hi:[1,0,1]
	v_cvt_pk_bf16_f32 v244, v228, v229
	v_cvt_pk_bf16_f32 v245, v230, v231
	global_store_dwordx2 v224, v[244:245], s[2:3]
	s_add_u32 s2, s2, 0x4000
	s_addc_u32 s3, s3, 0
	ds_read_b128 v[228:231], v222 offset:33792
	s_waitcnt vmcnt(15)
	v_lshlrev_b32_e32 v208, 16, v164
	v_and_b32_e32 v209, 0xffff0000, v164
	v_lshlrev_b32_e32 v210, 16, v165
	v_and_b32_e32 v211, 0xffff0000, v165
	s_waitcnt lgkmcnt(3)
	v_pk_fma_f32 v[232:233], v[208:209], s[22:23], v[232:233] op_sel_hi:[1,0,1]
	v_pk_fma_f32 v[234:235], v[210:211], s[22:23], v[234:235] op_sel_hi:[1,0,1]
	v_cvt_pk_bf16_f32 v226, v232, v233
	v_cvt_pk_bf16_f32 v227, v234, v235
	global_store_dwordx2 v224, v[226:227], s[2:3]
	s_add_u32 s2, s2, 0x4000
	s_addc_u32 s3, s3, 0
	ds_read_b128 v[232:235], v222 offset:38016
	s_waitcnt vmcnt(15)
	v_lshlrev_b32_e32 v204, 16, v166
	v_and_b32_e32 v205, 0xffff0000, v166
	v_lshlrev_b32_e32 v206, 16, v167
	v_and_b32_e32 v207, 0xffff0000, v167
	s_waitcnt lgkmcnt(3)
;   DI u16* y0b() const { return (u16*)(ws + WS_y0b); }
;   DI float* pre() const { return (float*)(ws + WS_pre); }
; DI float bflo(unsigned v) { return __uint_as_float(v << 16); }
; DI float bfhi(unsigned v) { return __uint_as_float(v & 0xffff0000u); }
; DI int otid() { int t = threadIdx.x; asm volatile("" : "+v"(t)); return t; }
; DI void st_bf4(u16* d, float a, float b, float c, float e) { *(uint2*)d = pack4(a, b, c, e); }
; template <int K, typename Epi>
; DI void gemm_tile_wide(const u16* __restrict__ A, int lda, const u16* __restrict__ Bt, int ldb, int m0, int n0, char* smem, Epi epi) {
;     ...
;   for (int half = 0; half < 2; ++half) {
;     __syncthreads();
;   const int tid = otid(), c4 = (tid & 31) * 4;
;   for (int pp = 0; pp < npass; ++pp) {
;     const int row = pp * 8 + (tid >> 5);
;     const int tok = mt * 128 + row0 + row;
;     const int col = nt * 128 + c4;
;     float4 v = *(const float4*)(Cs + row * CS_LD + c4);
;     float4 x;
;     if (layer == 0) { const f32x4 t = __builtin_nontemporal_load((const f32x4*)(tok < TP ? p.x_prompt + (size_t)tok * 1024 + col : p.x_sample + (size_t)(tok - TP) * 1024 + col)); x = make_float4(t[0], t[1], t[2], t[3]); }
;     else { const uint2 yb = *(const uint2*)(p.y0b() + (size_t)tok * 1024 + col); x = make_float4(bflo(yb.x), bfhi(yb.x), bflo(yb.y), bfhi(yb.y)); }
;     st_bf4((u16*)p.pre() + (size_t)tok * 1024 + col, ALPHA * x.x + v.x, ALPHA * x.y + v.y, ALPHA * x.z + v.z, ALPHA * x.w + v.w);
;   }
	v_pk_fma_f32 v[236:237], v[204:205], s[22:23], v[236:237] op_sel_hi:[1,0,1]
	v_pk_fma_f32 v[238:239], v[206:207], s[22:23], v[238:239] op_sel_hi:[1,0,1]
	v_cvt_pk_bf16_f32 v244, v236, v237
	v_cvt_pk_bf16_f32 v245, v238, v239
	global_store_dwordx2 v224, v[244:245], s[2:3]
	s_add_u32 s2, s2, 0x4000
	s_addc_u32 s3, s3, 0
	ds_read_b128 v[236:239], v222 offset:42240
	s_waitcnt vmcnt(15)
	v_lshlrev_b32_e32 v208, 16, v168
	v_and_b32_e32 v209, 0xffff0000, v168
	v_lshlrev_b32_e32 v210, 16, v169
	v_and_b32_e32 v211, 0xffff0000, v169
	s_waitcnt lgkmcnt(3)
	v_pk_fma_f32 v[240:241], v[208:209], s[22:23], v[240:241] op_sel_hi:[1,0,1]
	v_pk_fma_f32 v[242:243], v[210:211], s[22:23], v[242:243] op_sel_hi:[1,0,1]
	v_cvt_pk_bf16_f32 v226, v240, v241
	v_cvt_pk_bf16_f32 v227, v242, v243
	global_store_dwordx2 v224, v[226:227], s[2:3]
	s_add_u32 s2, s2, 0x4000
	s_addc_u32 s3, s3, 0
	ds_read_b128 v[240:243], v222 offset:46464
	s_waitcnt vmcnt(15)
	v_lshlrev_b32_e32 v204, 16, v170
	v_and_b32_e32 v205, 0xffff0000, v170
	v_lshlrev_b32_e32 v206, 16, v171
	v_and_b32_e32 v207, 0xffff0000, v171
	s_waitcnt lgkmcnt(3)
	v_pk_fma_f32 v[228:229], v[204:205], s[22:23], v[228:229] op_sel_hi:[1,0,1]
	v_pk_fma_f32 v[230:231], v[206:207], s[22:23], v[230:231] op_sel_hi:[1,0,1]
	v_cvt_pk_bf16_f32 v244, v228, v229
	v_cvt_pk_bf16_f32 v245, v230, v231
	global_store_dwordx2 v224, v[244:245], s[2:3]
	s_add_u32 s2, s2, 0x4000
	s_addc_u32 s3, s3, 0
	ds_read_b128 v[228:231], v222 offset:50688
	s_waitcnt vmcnt(15)
	v_lshlrev_b32_e32 v208, 16, v172
	v_and_b32_e32 v209, 0xffff0000, v172
	v_lshlrev_b32_e32 v210, 16, v173
	v_and_b32_e32 v211, 0xffff0000, v173
	s_waitcnt lgkmcnt(3)
	v_pk_fma_f32 v[232:233], v[208:209], s[22:23], v[232:233] op_sel_hi:[1,0,1]
	v_pk_fma_f32 v[234:235], v[210:211], s[22:23], v[234:235] op_sel_hi:[1,0,1]
	v_cvt_pk_bf16_f32 v226, v232, v233
	v_cvt_pk_bf16_f32 v227, v234, v235
	global_store_dwordx2 v224, v[226:227], s[2:3]
	s_add_u32 s2, s2, 0x4000
	s_addc_u32 s3, s3, 0
	ds_read_b128 v[232:235], v222 offset:54912
	s_waitcnt vmcnt(15)
	v_lshlrev_b32_e32 v204, 16, v174
	v_and_b32_e32 v205, 0xffff0000, v174
	v_lshlrev_b32_e32 v206, 16, v175
	v_and_b32_e32 v207, 0xffff0000, v175
	s_waitcnt lgkmcnt(3)
	v_pk_fma_f32 v[236:237], v[204:205], s[22:23], v[236:237] op_sel_hi:[1,0,1]
	v_pk_fma_f32 v[238:239], v[206:207], s[22:23], v[238:239] op_sel_hi:[1,0,1]
	v_cvt_pk_bf16_f32 v244, v236, v237
	v_cvt_pk_bf16_f32 v245, v238, v239
	global_store_dwordx2 v224, v[244:245], s[2:3]
	s_add_u32 s2, s2, 0x4000
	s_addc_u32 s3, s3, 0
	ds_read_b128 v[236:239], v222 offset:59136
	s_waitcnt vmcnt(15)
	v_lshlrev_b32_e32 v208, 16, v176
	v_and_b32_e32 v209, 0xffff0000, v176
	v_lshlrev_b32_e32 v210, 16, v177
	v_and_b32_e32 v211, 0xffff0000, v177
	s_waitcnt lgkmcnt(3)
	v_pk_fma_f32 v[240:241], v[208:209], s[22:23], v[240:241] op_sel_hi:[1,0,1]
	v_pk_fma_f32 v[242:243], v[210:211], s[22:23], v[242:243] op_sel_hi:[1,0,1]
	v_cvt_pk_bf16_f32 v226, v240, v241
	v_cvt_pk_bf16_f32 v227, v242, v243
	global_store_dwordx2 v224, v[226:227], s[2:3]
	s_add_u32 s2, s2, 0x4000
	s_addc_u32 s3, s3, 0
	ds_read_b128 v[240:243], v222 offset:63360
	s_waitcnt vmcnt(15)
	v_lshlrev_b32_e32 v204, 16, v178
	v_and_b32_e32 v205, 0xffff0000, v178
	v_lshlrev_b32_e32 v206, 16, v179
	v_and_b32_e32 v207, 0xffff0000, v179
	s_waitcnt lgkmcnt(3)
	v_pk_fma_f32 v[228:229], v[204:205], s[22:23], v[228:229] op_sel_hi:[1,0,1]
	v_pk_fma_f32 v[230:231], v[206:207], s[22:23], v[230:231] op_sel_hi:[1,0,1]
	v_cvt_pk_bf16_f32 v244, v228, v229
	v_cvt_pk_bf16_f32 v245, v230, v231
	global_store_dwordx2 v224, v[244:245], s[2:3]
	s_add_u32 s2, s2, 0x4000
	s_addc_u32 s3, s3, 0
	s_waitcnt vmcnt(15)
	v_lshlrev_b32_e32 v208, 16, v180
	v_and_b32_e32 v209, 0xffff0000, v180
	v_lshlrev_b32_e32 v210, 16, v181
	v_and_b32_e32 v211, 0xffff0000, v181
	s_waitcnt lgkmcnt(2)
	v_pk_fma_f32 v[232:233], v[208:209], s[22:23], v[232:233] op_sel_hi:[1,0,1]
	v_pk_fma_f32 v[234:235], v[210:211], s[22:23], v[234:235] op_sel_hi:[1,0,1]
	v_cvt_pk_bf16_f32 v226, v232, v233
	v_cvt_pk_bf16_f32 v227, v234, v235
	global_store_dwordx2 v224, v[226:227], s[2:3]
	s_add_u32 s2, s2, 0x4000
	s_addc_u32 s3, s3, 0
	s_waitcnt vmcnt(15)
	v_lshlrev_b32_e32 v204, 16, v182
	v_and_b32_e32 v205, 0xffff0000, v182
	v_lshlrev_b32_e32 v206, 16, v183
	v_and_b32_e32 v207, 0xffff0000, v183
	s_waitcnt lgkmcnt(1)
	v_pk_fma_f32 v[236:237], v[204:205], s[22:23], v[236:237] op_sel_hi:[1,0,1]
	v_pk_fma_f32 v[238:239], v[206:207], s[22:23], v[238:239] op_sel_hi:[1,0,1]
	v_cvt_pk_bf16_f32 v244, v236, v237
	v_cvt_pk_bf16_f32 v245, v238, v239
	global_store_dwordx2 v224, v[244:245], s[2:3]
	s_add_u32 s2, s2, 0x4000
	s_addc_u32 s3, s3, 0
	s_waitcnt vmcnt(15)
	v_lshlrev_b32_e32 v208, 16, v184
	v_and_b32_e32 v209, 0xffff0000, v184
	v_lshlrev_b32_e32 v210, 16, v185
	v_and_b32_e32 v211, 0xffff0000, v185
	s_waitcnt lgkmcnt(0)
	v_pk_fma_f32 v[240:241], v[208:209], s[22:23], v[240:241] op_sel_hi:[1,0,1]
	v_pk_fma_f32 v[242:243], v[210:211], s[22:23], v[242:243] op_sel_hi:[1,0,1]
	v_cvt_pk_bf16_f32 v226, v240, v241
	v_cvt_pk_bf16_f32 v227, v242, v243
	global_store_dwordx2 v224, v[226:227], s[2:3]
	s_barrier
; DI int crow(int reg, int h) { return (reg & 3) + 8 * (reg >> 2) + 4 * h; }
; template <int K, typename Epi>
; DI void gemm_tile_wide(const u16* __restrict__ A, int lda, const u16* __restrict__ Bt, int ldb, int m0, int n0, char* smem, Epi epi) {
;     ...
;     __syncthreads();
;     if (wn == half) {
; #pragma unroll
;       for (int i = 0; i < 2; ++i)
; #pragma unroll
;         for (int j = 0; j < 4; ++j)
; #pragma unroll
;           for (int e = 0; e < 16; ++e) Cs[(wm * 64 + i * 32 + crow(e, h)) * CS_LD + j * 32 + r] = acc[i][j][e];
;     }
	s_and_saveexec_b64 s[0:1], vcc
	s_cbranch_execz .LBB0_2049
	v_mad_u64_u32 v[130:131], s[2:3], v131, s26, v[130:131]
	ds_write2_b32 v130, v0, v48 offset1:32
	ds_write2_b32 v130, v1, v49 offset0:132 offset1:164
	v_add_u32_e32 v0, 0x400, v130
	ds_write2_b32 v0, v2, v50 offset0:8 offset1:40
	ds_write2_b32 v0, v3, v51 offset0:140 offset1:172
	v_add_u32_e32 v1, 0x1000, v130
	v_add_u32_e32 v2, 0x1400, v130
	ds_write2_b32 v1, v4, v52 offset0:32 offset1:64
	ds_write2_b32 v1, v5, v53 offset0:164 offset1:196
	ds_write2_b32 v2, v6, v54 offset0:40 offset1:72
	ds_write2_b32 v2, v7, v55 offset0:172 offset1:204
	v_add_u32_e32 v3, 0x2000, v130
	v_add_u32_e32 v4, 0x2400, v130
	v_add_u32_e32 v6, 0x3200, v130
	ds_write2_b32 v3, v8, v56 offset0:64 offset1:96
	ds_write2_b32 v3, v9, v57 offset0:196 offset1:228
	ds_write2_b32 v4, v10, v58 offset0:72 offset1:104
	ds_write2_b32 v4, v11, v59 offset0:204 offset1:236
	v_add_u32_e32 v5, 0x3000, v130
	ds_write2_b32 v6, v13, v61 offset0:100 offset1:132
	v_add_u32_e32 v6, 0x3400, v130
	v_add_u32_e32 v7, 0x3600, v130
	ds_write2_b32 v5, v12, v60 offset0:96 offset1:128
	ds_write2_b32 v6, v14, v62 offset0:104 offset1:136
	ds_write2_b32 v7, v15, v63 offset0:108 offset1:140
	ds_write2_b32 v130, v16, v64 offset0:64 offset1:96
	ds_write2_b32 v130, v17, v65 offset0:196 offset1:228
	ds_write2_b32 v0, v18, v66 offset0:72 offset1:104
	ds_write2_b32 v0, v19, v67 offset0:204 offset1:236
	ds_write2_b32 v1, v20, v68 offset0:96 offset1:128
	v_add_u32_e32 v0, 0x1200, v130
	ds_write2_b32 v0, v21, v69 offset0:100 offset1:132
	ds_write2_b32 v2, v22, v70 offset0:104 offset1:136
	v_add_u32_e32 v0, 0x1600, v130
	ds_write2_b32 v0, v23, v71 offset0:108 offset1:140
	ds_write2_b32 v3, v24, v72 offset0:128 offset1:160
	ds_write2_b32 v4, v25, v73 offset0:4 offset1:36
	ds_write2_b32 v4, v26, v74 offset0:136 offset1:168
	v_add_u32_e32 v0, 0x2800, v130
	ds_write2_b32 v0, v27, v75 offset0:12 offset1:44
	ds_write2_b32 v5, v28, v76 offset0:160 offset1:192
	ds_write2_b32 v6, v29, v77 offset0:36 offset1:68
	ds_write2_b32 v6, v30, v78 offset0:168 offset1:200
	v_add_u32_e32 v0, 0x3800, v130
	ds_write2_b32 v0, v31, v79 offset0:44 offset1:76
	v_add_u32_e32 v0, 0x4000, v130
	v_add_u32_e32 v1, 0x4400, v130
	v_add_u32_e32 v3, 0x5000, v130
	ds_write2_b32 v0, v32, v96 offset0:128 offset1:160
	ds_write2_b32 v1, v33, v97 offset0:4 offset1:36
	ds_write2_b32 v1, v34, v98 offset0:136 offset1:168
	v_add_u32_e32 v2, 0x4800, v130
	ds_write2_b32 v3, v36, v100 offset0:160 offset1:192
	v_add_u32_e32 v3, 0x5400, v130
	v_add_u32_e32 v5, 0x6000, v130
	ds_write2_b32 v2, v35, v99 offset0:12 offset1:44
	ds_write2_b32 v3, v37, v101 offset0:36 offset1:68
	ds_write2_b32 v3, v38, v102 offset0:168 offset1:200
	v_add_u32_e32 v4, 0x5800, v130
	ds_write2_b32 v5, v40, v104 offset0:192 offset1:224
	v_add_u32_e32 v5, 0x6400, v130
	v_add_u32_e32 v7, 0x7200, v130
	v_add_u32_e32 v8, 0x7600, v130
	ds_write2_b32 v4, v39, v103 offset0:44 offset1:76
	ds_write2_b32 v5, v41, v105 offset0:68 offset1:100
	ds_write2_b32 v5, v42, v106 offset0:200 offset1:232
	v_add_u32_e32 v6, 0x6800, v130
	ds_write2_b32 v7, v44, v108 offset0:96 offset1:128
	v_add_u32_e32 v7, 0x7400, v130
	ds_write2_b32 v8, v46, v110 offset0:104 offset1:136
	v_add_u32_e32 v8, 0x7800, v130
	ds_write2_b32 v6, v43, v107 offset0:76 offset1:108
	ds_write2_b32 v7, v45, v109 offset0:100 offset1:132
	ds_write2_b32 v8, v47, v111 offset0:108 offset1:140
	ds_write2_b32 v0, v80, v112 offset0:192 offset1:224
	ds_write2_b32 v1, v81, v113 offset0:68 offset1:100
	ds_write2_b32 v1, v82, v114 offset0:200 offset1:232
	ds_write2_b32 v2, v83, v115 offset0:76 offset1:108
	v_add_u32_e32 v0, 0x5200, v130
	ds_write2_b32 v0, v84, v116 offset0:96 offset1:128
	ds_write2_b32 v3, v85, v117 offset0:100 offset1:132
	v_add_u32_e32 v0, 0x5600, v130
	ds_write2_b32 v0, v86, v118 offset0:104 offset1:136
	ds_write2_b32 v4, v87, v119 offset0:108 offset1:140
	ds_write2_b32 v5, v88, v120 offset1:32
	ds_write2_b32 v5, v89, v121 offset0:132 offset1:164
	ds_write2_b32 v6, v90, v122 offset0:8 offset1:40
	ds_write2_b32 v6, v91, v123 offset0:140 offset1:172
	ds_write2_b32 v7, v92, v124 offset0:32 offset1:64
	ds_write2_b32 v7, v93, v125 offset0:164 offset1:196
	ds_write2_b32 v8, v94, v126 offset0:40 offset1:72
	ds_write2_b32 v8, v95, v127 offset0:172 offset1:204
	s_branch .LBB0_2049
